# MLA attention loop: K-fragment reads pipelined 3 pairs ahead, the 5 per-tile LDS-DMA issues spread across QK/softmax/PV instead of all at the tile top
# baseline (speedup 1.0000x reference)
.LBB0_1425:
	s_add_i32 s13, s74, 0x8000
	s_mov_b32 s14, m0
	s_mov_b32 m0, s13
	s_nop 0
	global_load_lds_dwordx4 v[168:169], off
	s_mov_b32 m0, s14
	ds_read_b128 v[178:181], v211
	ds_read_b128 v[214:217], v211 offset:12288
	ds_read_b128 v[238:241], v210
	ds_read_b128 v[242:245], v210 offset:12288
	ds_read_b128 v[246:249], v209
	ds_read_b128 v[250:253], v209 offset:12288
	ds_read_b128 v[218:221], v193
	ds_read_b128 v[222:225], v193 offset:1024
	ds_read_b128 v[226:229], v193 offset:2048
	ds_read_b128 v[230:233], v193 offset:3072
	s_waitcnt lgkmcnt(9)
	v_mfma_f32_32x32x16_bf16 v[114:129], v[178:181], v[158:161], v[82:97]
	s_waitcnt lgkmcnt(8)
	v_mfma_f32_32x32x16_bf16 v[98:113], v[214:217], v[158:161], v[82:97]
	ds_read_b128 v[178:181], v208
	ds_read_b128 v[214:217], v208 offset:12288
	s_waitcnt lgkmcnt(9)
	v_mfma_f32_32x32x16_bf16 v[114:129], v[238:241], v[154:157], v[114:129]
	s_waitcnt lgkmcnt(8)
	v_mfma_f32_32x32x16_bf16 v[98:113], v[242:245], v[154:157], v[98:113]
	ds_read_b128 v[238:241], v207
	ds_read_b128 v[242:245], v207 offset:12288
	s_waitcnt lgkmcnt(9)
	v_mfma_f32_32x32x16_bf16 v[114:129], v[246:249], v[150:153], v[114:129]
	s_waitcnt lgkmcnt(8)
	v_mfma_f32_32x32x16_bf16 v[98:113], v[250:253], v[150:153], v[98:113]
	ds_read_b128 v[246:249], v206
	ds_read_b128 v[250:253], v206 offset:12288
	s_waitcnt lgkmcnt(5)
	v_mfma_f32_32x32x16_bf16 v[114:129], v[178:181], v[146:149], v[114:129]
	s_waitcnt lgkmcnt(4)
	v_mfma_f32_32x32x16_bf16 v[98:113], v[214:217], v[146:149], v[98:113]
	ds_read_b128 v[178:181], v205
	ds_read_b128 v[214:217], v205 offset:12288
	s_waitcnt lgkmcnt(5)
	v_mfma_f32_32x32x16_bf16 v[114:129], v[238:241], v[142:145], v[114:129]
	s_waitcnt lgkmcnt(4)
	v_mfma_f32_32x32x16_bf16 v[98:113], v[242:245], v[142:145], v[98:113]
	ds_read_b128 v[238:241], v204
	ds_read_b128 v[242:245], v204 offset:12288
	s_waitcnt lgkmcnt(5)
	v_mfma_f32_32x32x16_bf16 v[114:129], v[246:249], v[138:141], v[114:129]
	s_waitcnt lgkmcnt(4)
	v_mfma_f32_32x32x16_bf16 v[98:113], v[250:253], v[138:141], v[98:113]
	ds_read_b128 v[246:249], v203
	ds_read_b128 v[250:253], v203 offset:12288
	s_add_i32 s13, s75, 0x8000
	s_mov_b32 s14, m0
	s_mov_b32 m0, s13
	s_nop 0
	global_load_lds_dwordx4 v[170:171], off
	s_mov_b32 m0, s14
	s_waitcnt lgkmcnt(5)
	v_mfma_f32_32x32x16_bf16 v[114:129], v[178:181], v[134:137], v[114:129]
	s_waitcnt lgkmcnt(4)
	v_mfma_f32_32x32x16_bf16 v[98:113], v[214:217], v[134:137], v[98:113]
	ds_read_b128 v[178:181], v202
	ds_read_b128 v[214:217], v202 offset:12288
	s_waitcnt lgkmcnt(5)
	v_mfma_f32_32x32x16_bf16 v[114:129], v[238:241], v[130:133], v[114:129]
	s_waitcnt lgkmcnt(4)
	v_mfma_f32_32x32x16_bf16 v[98:113], v[242:245], v[130:133], v[98:113]
	ds_read_b128 v[238:241], v201
	ds_read_b128 v[242:245], v201 offset:12288
	s_waitcnt lgkmcnt(5)
	v_mfma_f32_32x32x16_bf16 v[114:129], v[246:249], v[218:221], v[114:129]
	s_waitcnt lgkmcnt(4)
	v_mfma_f32_32x32x16_bf16 v[98:113], v[250:253], v[218:221], v[98:113]
	ds_read_b128 v[246:249], v200
	ds_read_b128 v[250:253], v200 offset:12288
	s_waitcnt lgkmcnt(5)
	v_mfma_f32_32x32x16_bf16 v[114:129], v[178:181], v[222:225], v[114:129]
	s_waitcnt lgkmcnt(4)
	v_mfma_f32_32x32x16_bf16 v[98:113], v[214:217], v[222:225], v[98:113]
	s_waitcnt lgkmcnt(3)
	v_mfma_f32_32x32x16_bf16 v[114:129], v[238:241], v[226:229], v[114:129]
	s_waitcnt lgkmcnt(2)
	v_mfma_f32_32x32x16_bf16 v[98:113], v[242:245], v[226:229], v[98:113]
	s_waitcnt lgkmcnt(1)
	v_mfma_f32_32x32x16_bf16 v[114:129], v[246:249], v[230:233], v[114:129]
	s_waitcnt lgkmcnt(0)
	v_mfma_f32_32x32x16_bf16 v[98:113], v[250:253], v[230:233], v[98:113]
	s_add_i32 s13, s5, 0x8000
	s_mov_b32 s14, m0
	s_mov_b32 m0, s13
	s_nop 0
	global_load_lds_dwordx4 v[172:173], off
	s_mov_b32 m0, s14
	s_sub_i32 s0, s12, 64
	s_cmp_le_i32 s0, s96
	s_cbranch_scc1 .LBB0_1427
	v_add_u32_e32 v165, 0x5b, v212
	v_cmp_lt_i32_e32 vcc, -1, v165
	s_nop 4
	v_cndmask_b32_e32 v114, v185, v114, vcc
	v_cmp_lt_i32_e32 vcc, 31, v165
	v_add_u32_e32 v165, 0x5a, v212
	s_nop 0
	v_cndmask_b32_e32 v98, v185, v98, vcc
	v_cmp_lt_i32_e32 vcc, -1, v165
	s_nop 1
	v_cndmask_b32_e32 v115, v185, v115, vcc
	v_cmp_lt_i32_e32 vcc, 31, v165
	v_add_u32_e32 v165, 0x59, v212
	s_nop 0
	v_cndmask_b32_e32 v99, v185, v99, vcc
	v_cmp_lt_i32_e32 vcc, -1, v165
	s_nop 1
	v_cndmask_b32_e32 v116, v185, v116, vcc
	v_cmp_lt_i32_e32 vcc, 31, v165
	v_add_u32_e32 v165, 0x58, v212
	s_nop 0
	v_cndmask_b32_e32 v100, v185, v100, vcc
	v_cmp_lt_i32_e32 vcc, -1, v165
	s_nop 1
	v_cndmask_b32_e32 v117, v185, v117, vcc
	v_cmp_lt_i32_e32 vcc, 31, v165
	v_add_u32_e32 v165, 0x53, v212
	s_nop 0
	v_cndmask_b32_e32 v101, v185, v101, vcc
	v_cmp_lt_i32_e32 vcc, -1, v165
	s_nop 1
	v_cndmask_b32_e32 v118, v185, v118, vcc
	v_cmp_lt_i32_e32 vcc, 31, v165
	v_add_u32_e32 v165, 0x52, v212
	s_nop 0
	v_cndmask_b32_e32 v102, v185, v102, vcc
	v_cmp_lt_i32_e32 vcc, -1, v165
	s_nop 1
	v_cndmask_b32_e32 v119, v185, v119, vcc
	v_cmp_lt_i32_e32 vcc, 31, v165
	v_add_u32_e32 v165, 0x51, v212
	s_nop 0
	v_cndmask_b32_e32 v103, v185, v103, vcc
	v_cmp_lt_i32_e32 vcc, -1, v165
	s_nop 1
	v_cndmask_b32_e32 v120, v185, v120, vcc
	v_cmp_lt_i32_e32 vcc, 31, v165
	v_add_u32_e32 v165, 0x50, v212
	s_nop 0
	v_cndmask_b32_e32 v104, v185, v104, vcc
	v_cmp_lt_i32_e32 vcc, -1, v165
	s_nop 1
	v_cndmask_b32_e32 v121, v185, v121, vcc
	v_cmp_lt_i32_e32 vcc, 31, v165
	v_add_u32_e32 v165, 0x4b, v212
	s_nop 0
	v_cndmask_b32_e32 v105, v185, v105, vcc
	v_cmp_lt_i32_e32 vcc, -1, v165
	s_nop 1
	v_cndmask_b32_e32 v122, v185, v122, vcc
	v_cmp_lt_i32_e32 vcc, 31, v165
	v_add_u32_e32 v165, 0x4a, v212
	s_nop 0
	v_cndmask_b32_e32 v106, v185, v106, vcc
	v_cmp_lt_i32_e32 vcc, -1, v165
	s_nop 1
	v_cndmask_b32_e32 v123, v185, v123, vcc
	v_cmp_lt_i32_e32 vcc, 31, v165
	v_add_u32_e32 v165, 0x49, v212
	s_nop 0
	v_cndmask_b32_e32 v107, v185, v107, vcc
	v_cmp_lt_i32_e32 vcc, -1, v165
	s_nop 1
	v_cndmask_b32_e32 v124, v185, v124, vcc
	v_cmp_lt_i32_e32 vcc, 31, v165
	v_add_u32_e32 v165, 0x48, v212
	s_nop 0
	v_cndmask_b32_e32 v108, v185, v108, vcc
	v_cmp_lt_i32_e32 vcc, -1, v165
	s_nop 1
	v_cndmask_b32_e32 v125, v185, v125, vcc
	v_cmp_lt_i32_e32 vcc, 31, v165
	v_add_u32_e32 v165, 0x43, v212
	s_nop 0
	v_cndmask_b32_e32 v109, v185, v109, vcc
	v_cmp_lt_i32_e32 vcc, -1, v165
	s_nop 1
	v_cndmask_b32_e32 v126, v185, v126, vcc
	v_cmp_lt_i32_e32 vcc, 31, v165
	v_add_u32_e32 v165, 0x42, v212
	s_nop 0
	v_cndmask_b32_e32 v110, v185, v110, vcc
	v_cmp_lt_i32_e32 vcc, -1, v165
	s_nop 1
	v_cndmask_b32_e32 v127, v185, v127, vcc
	v_cmp_lt_i32_e32 vcc, 31, v165
	v_add_u32_e32 v165, 0x41, v212
	s_nop 0
	v_cndmask_b32_e32 v111, v185, v111, vcc
	v_cmp_lt_i32_e32 vcc, -1, v165
	s_nop 1
	v_cndmask_b32_e32 v128, v185, v128, vcc
	v_cmp_lt_i32_e32 vcc, 31, v165
	v_add_u32_e32 v165, 64, v212
	s_nop 0
	v_cndmask_b32_e32 v112, v185, v112, vcc
	v_cmp_lt_i32_e32 vcc, -1, v165
	s_nop 1
	v_cndmask_b32_e32 v129, v185, v129, vcc
	v_cmp_lt_i32_e32 vcc, 31, v165
	s_nop 1
	v_cndmask_b32_e32 v113, v185, v113, vcc

.LBB0_1431:
	v_exp_f32_e32 v114, v114
	v_exp_f32_e32 v215, v98
	v_exp_f32_e32 v98, v115
	v_exp_f32_e32 v115, v99
	v_exp_f32_e32 v99, v116
	v_exp_f32_e32 v116, v100
	v_exp_f32_e32 v100, v117
	v_exp_f32_e32 v117, v101
	v_exp_f32_e32 v101, v118
	v_exp_f32_e32 v118, v102
	v_exp_f32_e32 v102, v119
	v_exp_f32_e32 v119, v103
	v_exp_f32_e32 v103, v120
	v_exp_f32_e32 v120, v104
	v_exp_f32_e32 v104, v121
	v_exp_f32_e32 v121, v105
	v_exp_f32_e32 v105, v122
	v_exp_f32_e32 v122, v106
	v_exp_f32_e32 v106, v123
	v_exp_f32_e32 v123, v107
	v_exp_f32_e32 v107, v124
	v_exp_f32_e32 v124, v108
	v_exp_f32_e32 v108, v125
	v_exp_f32_e32 v125, v109
	v_exp_f32_e32 v109, v126
	v_exp_f32_e32 v126, v110
	v_exp_f32_e32 v110, v127
	v_exp_f32_e32 v127, v111
	v_exp_f32_e32 v111, v128
	v_exp_f32_e32 v128, v112
	v_exp_f32_e32 v112, v129
	v_add_f32_e32 v129, v114, v215
	v_add_f32_e32 v213, v98, v115
	v_add_f32_e32 v214, v99, v116
	v_add_f32_e32 v216, v100, v117
	v_exp_f32_e32 v113, v113
	v_add_f32_e32 v129, v129, v101
	v_add_f32_e32 v213, v213, v102
	v_add_f32_e32 v214, v214, v103
	v_add_f32_e32 v216, v216, v104
	v_mov_b32_e32 v165, v163
	v_add_f32_e32 v129, v129, v118
	v_add_f32_e32 v213, v213, v119
	v_add_f32_e32 v214, v214, v120
	v_add_f32_e32 v216, v216, v121
	v_mov_b32_e32 v167, v163
	v_add_f32_e32 v129, v129, v105
	v_add_f32_e32 v213, v213, v106
	v_add_f32_e32 v214, v214, v107
	v_add_f32_e32 v216, v216, v108
	v_lshl_add_u64 v[168:169], v[168:169], 0, v[162:163]
	v_add_f32_e32 v129, v129, v122
	v_add_f32_e32 v213, v213, v123
	v_add_f32_e32 v214, v214, v124
	v_add_f32_e32 v216, v216, v125
	v_lshl_add_u64 v[170:171], v[170:171], 0, v[164:165]
	v_add_f32_e32 v129, v129, v109
	v_add_f32_e32 v213, v213, v110
	v_add_f32_e32 v214, v214, v111
	v_add_f32_e32 v216, v216, v112
	v_lshl_add_u64 v[172:173], v[172:173], 0, v[166:167]
	v_add_f32_e32 v129, v129, v126
	v_add_f32_e32 v213, v213, v127
	v_add_f32_e32 v214, v214, v128
	v_add_f32_e32 v216, v216, v113
	v_lshl_add_u64 v[180:181], v[174:175], 0, s[76:77]
	v_add_f32_e32 v129, v129, v213
	v_add_f32_e32 v213, v214, v216
	v_lshl_add_u64 v[178:179], v[176:177], 0, s[76:77]
	v_add_f32_e32 v213, v129, v213
	v_cvt_pk_bf16_f32 v98, v114, v98
	v_cvt_pk_bf16_f32 v99, v99, v100
	v_cvt_pk_bf16_f32 v100, v101, v102
	v_cvt_pk_bf16_f32 v101, v103, v104
	v_cvt_pk_bf16_f32 v102, v105, v106
	s_nop 0
	v_mov_b32_e32 v214, v213
	s_nop 1
	v_permlane32_swap_b32_e32 v213, v214
	v_cvt_pk_bf16_f32 v103, v107, v108
	v_cvt_pk_bf16_f32 v104, v109, v110
	v_cvt_pk_bf16_f32 v105, v111, v112
	v_cvt_pk_bf16_f32 v106, v215, v115
	v_cvt_pk_bf16_f32 v107, v116, v117
	v_cvt_pk_bf16_f32 v108, v118, v119
	v_cvt_pk_bf16_f32 v109, v120, v121
	v_cvt_pk_bf16_f32 v110, v122, v123
	v_cvt_pk_bf16_f32 v111, v124, v125
	v_cvt_pk_bf16_f32 v112, v126, v127
	v_cvt_pk_bf16_f32 v113, v128, v113
	v_permlane32_swap_b32_e32 v98, v100
	v_permlane32_swap_b32_e32 v99, v101
	v_permlane32_swap_b32_e32 v102, v104
	v_permlane32_swap_b32_e32 v103, v105
	v_permlane32_swap_b32_e32 v106, v108
	v_permlane32_swap_b32_e32 v107, v109
	v_permlane32_swap_b32_e32 v110, v112
	v_permlane32_swap_b32_e32 v111, v113
	s_add_i32 s13, s86, 0x0
	s_mov_b32 s14, m0
	s_mov_b32 m0, s13
	s_nop 0
	global_load_lds_dwordx4 v[174:175], off
	s_mov_b32 m0, s14
	ds_read_b64_tr_b16 v[114:115], v190 offset:0x4000
	ds_read_b64_tr_b16 v[116:117], v190 offset:0x4800
	ds_read_b64_tr_b16 v[118:119], v190 offset:0x5000
	ds_read_b64_tr_b16 v[120:121], v190 offset:0x5800
	ds_read_b64_tr_b16 v[122:123], v190 offset:0x6000
	ds_read_b64_tr_b16 v[124:125], v190 offset:0x6800
	ds_read_b64_tr_b16 v[126:127], v190 offset:0x7000
	ds_read_b64_tr_b16 v[128:129], v190 offset:0x7800
	ds_read_b64_tr_b16 v[216:217], v190 offset:0x4200
	ds_read_b64_tr_b16 v[218:219], v190 offset:0x4a00
	ds_read_b64_tr_b16 v[220:221], v190 offset:0x5200
	ds_read_b64_tr_b16 v[222:223], v190 offset:0x5a00
	ds_read_b64_tr_b16 v[224:225], v190 offset:0x6200
	ds_read_b64_tr_b16 v[226:227], v190 offset:0x6a00
	ds_read_b64_tr_b16 v[228:229], v190 offset:0x7200
	ds_read_b64_tr_b16 v[230:231], v190 offset:0x7a00
	s_waitcnt lgkmcnt(8)
	s_nop 0
	v_mfma_f32_32x32x16_bf16 v[18:33], v[98:101], v[114:117], v[18:33]
	v_mfma_f32_32x32x16_bf16 v[18:33], v[102:105], v[118:121], v[18:33]
	v_mfma_f32_32x32x16_bf16 v[18:33], v[106:109], v[122:125], v[18:33]
	v_mfma_f32_32x32x16_bf16 v[18:33], v[110:113], v[126:129], v[18:33]
	s_add_i32 s13, s3, 0x0
	s_mov_b32 s14, m0
	s_mov_b32 m0, s13
	s_nop 0
	global_load_lds_dwordx4 v[176:177], off
	s_mov_b32 m0, s14
	ds_read_b64_tr_b16 v[114:115], v190 offset:0x4400
	ds_read_b64_tr_b16 v[116:117], v190 offset:0x4c00
	ds_read_b64_tr_b16 v[118:119], v190 offset:0x5400
	ds_read_b64_tr_b16 v[120:121], v190 offset:0x5c00
	ds_read_b64_tr_b16 v[122:123], v190 offset:0x6400
	ds_read_b64_tr_b16 v[124:125], v190 offset:0x6c00
	ds_read_b64_tr_b16 v[126:127], v190 offset:0x7400
	ds_read_b64_tr_b16 v[128:129], v190 offset:0x7c00
	s_waitcnt lgkmcnt(8)
	v_mfma_f32_32x32x16_bf16 v[34:49], v[98:101], v[216:219], v[34:49]
	v_mfma_f32_32x32x16_bf16 v[34:49], v[102:105], v[220:223], v[34:49]
	v_mfma_f32_32x32x16_bf16 v[34:49], v[106:109], v[224:227], v[34:49]
	v_mfma_f32_32x32x16_bf16 v[34:49], v[110:113], v[228:231], v[34:49]
	ds_read_b64_tr_b16 v[216:217], v190 offset:0x4600
	ds_read_b64_tr_b16 v[218:219], v190 offset:0x4e00
	ds_read_b64_tr_b16 v[220:221], v190 offset:0x5600
	ds_read_b64_tr_b16 v[222:223], v190 offset:0x5e00
	ds_read_b64_tr_b16 v[224:225], v190 offset:0x6600
	ds_read_b64_tr_b16 v[226:227], v190 offset:0x6e00
	ds_read_b64_tr_b16 v[228:229], v190 offset:0x7600
	ds_read_b64_tr_b16 v[230:231], v190 offset:0x7e00
	s_waitcnt lgkmcnt(8)
	v_mfma_f32_32x32x16_bf16 v[50:65], v[98:101], v[114:117], v[50:65]
	v_mfma_f32_32x32x16_bf16 v[50:65], v[102:105], v[118:121], v[50:65]
	v_mfma_f32_32x32x16_bf16 v[50:65], v[106:109], v[122:125], v[50:65]
	v_mfma_f32_32x32x16_bf16 v[50:65], v[110:113], v[126:129], v[50:65]
	s_waitcnt lgkmcnt(0)
	v_mfma_f32_32x32x16_bf16 v[66:81], v[98:101], v[216:219], v[66:81]
	s_waitcnt vmcnt(0)
	s_cmp_lt_u32 s11, s10
	s_cselect_b64 s[0:1], -1, 0
	s_cmp_ge_u32 s11, s10
	s_barrier
	v_mfma_f32_32x32x16_bf16 v[66:81], v[102:105], v[220:223], v[66:81]
	v_mfma_f32_32x32x16_bf16 v[66:81], v[106:109], v[224:227], v[66:81]
	v_mfma_f32_32x32x16_bf16 v[66:81], v[110:113], v[228:231], v[66:81]
	s_cbranch_scc1 .LBB0_1433
	s_add_i32 s13, s86, 0x4000
	s_mov_b32 s14, m0
	s_mov_b32 m0, s13
	s_nop 0
	global_load_lds_dwordx4 v[180:181], off
	s_mov_b32 m0, s14
	s_add_i32 s13, s3, 0x4000
	s_mov_b32 s14, m0
	s_mov_b32 m0, s13
	s_nop 0
	global_load_lds_dwordx4 v[178:179], off
	s_mov_b32 m0, s14
	v_lshl_add_u64 v[174:175], v[174:175], 0, s[30:31]
	v_lshl_add_u64 v[176:177], v[176:177], 0, s[30:31]
	s_branch .LBB0_1434

.LBB0_1434:
	ds_read_b128 v[178:181], v194 offset:32768
	ds_read_b128 v[216:219], v194 offset:45056
	ds_read_b128 v[238:241], v195 offset:32768
	ds_read_b128 v[242:245], v195 offset:45056
	ds_read_b128 v[246:249], v196 offset:32768
	ds_read_b128 v[250:253], v196 offset:45056
	ds_read_b128 v[220:223], v193
	ds_read_b128 v[224:227], v193 offset:1024
	ds_read_b128 v[228:231], v193 offset:2048
	ds_read_b128 v[232:235], v193 offset:3072
	s_waitcnt lgkmcnt(9)
	v_mfma_f32_32x32x16_bf16 v[114:129], v[178:181], v[158:161], v[82:97]
	s_waitcnt lgkmcnt(8)
	v_mfma_f32_32x32x16_bf16 v[98:113], v[216:219], v[158:161], v[82:97]
	ds_read_b128 v[178:181], v197 offset:32768
	ds_read_b128 v[216:219], v197 offset:45056
	s_waitcnt lgkmcnt(9)
	v_mfma_f32_32x32x16_bf16 v[114:129], v[238:241], v[154:157], v[114:129]
	s_waitcnt lgkmcnt(8)
	v_mfma_f32_32x32x16_bf16 v[98:113], v[242:245], v[154:157], v[98:113]
	ds_read_b128 v[238:241], v194 offset:32896
	ds_read_b128 v[242:245], v194 offset:45184
	s_waitcnt lgkmcnt(9)
	v_mfma_f32_32x32x16_bf16 v[114:129], v[246:249], v[150:153], v[114:129]
	s_waitcnt lgkmcnt(8)
	v_mfma_f32_32x32x16_bf16 v[98:113], v[250:253], v[150:153], v[98:113]
	ds_read_b128 v[246:249], v195 offset:32896
	ds_read_b128 v[250:253], v195 offset:45184
	s_waitcnt lgkmcnt(5)
	v_mfma_f32_32x32x16_bf16 v[114:129], v[178:181], v[146:149], v[114:129]
	s_waitcnt lgkmcnt(4)
	v_mfma_f32_32x32x16_bf16 v[98:113], v[216:219], v[146:149], v[98:113]
	ds_read_b128 v[178:181], v196 offset:32896
	ds_read_b128 v[216:219], v196 offset:45184
	s_waitcnt lgkmcnt(5)
	v_mfma_f32_32x32x16_bf16 v[114:129], v[238:241], v[142:145], v[114:129]
	s_waitcnt lgkmcnt(4)
	v_mfma_f32_32x32x16_bf16 v[98:113], v[242:245], v[142:145], v[98:113]
	ds_read_b128 v[238:241], v197 offset:32896
	ds_read_b128 v[242:245], v197 offset:45184
	s_waitcnt lgkmcnt(5)
	v_mfma_f32_32x32x16_bf16 v[114:129], v[246:249], v[138:141], v[114:129]
	s_waitcnt lgkmcnt(4)
	v_mfma_f32_32x32x16_bf16 v[98:113], v[250:253], v[138:141], v[98:113]
	ds_read_b128 v[246:249], v194 offset:33024
	ds_read_b128 v[250:253], v194 offset:45312
	s_cmp_ge_u32 s11, s10
	s_cbranch_scc1 .Lspr_k1
	s_add_i32 s13, s74, 0xe000
	s_mov_b32 s14, m0
	s_mov_b32 m0, s13
	s_nop 0
	global_load_lds_dwordx4 v[168:169], off
	s_mov_b32 m0, s14
.Lspr_k1:
	s_waitcnt lgkmcnt(5)
	v_mfma_f32_32x32x16_bf16 v[114:129], v[178:181], v[134:137], v[114:129]
	s_waitcnt lgkmcnt(4)
	v_mfma_f32_32x32x16_bf16 v[98:113], v[216:219], v[134:137], v[98:113]
	ds_read_b128 v[178:181], v195 offset:33024
	ds_read_b128 v[216:219], v195 offset:45312
	s_waitcnt lgkmcnt(5)
	v_mfma_f32_32x32x16_bf16 v[114:129], v[238:241], v[130:133], v[114:129]
	s_waitcnt lgkmcnt(4)
	v_mfma_f32_32x32x16_bf16 v[98:113], v[242:245], v[130:133], v[98:113]
	ds_read_b128 v[238:241], v196 offset:33024
	ds_read_b128 v[242:245], v196 offset:45312
	s_waitcnt lgkmcnt(5)
	v_mfma_f32_32x32x16_bf16 v[114:129], v[246:249], v[220:223], v[114:129]
	s_waitcnt lgkmcnt(4)
	v_mfma_f32_32x32x16_bf16 v[98:113], v[250:253], v[220:223], v[98:113]
	ds_read_b128 v[246:249], v197 offset:33024
	ds_read_b128 v[250:253], v197 offset:45312
	s_waitcnt lgkmcnt(5)
	v_mfma_f32_32x32x16_bf16 v[114:129], v[178:181], v[224:227], v[114:129]
	s_waitcnt lgkmcnt(4)
	v_mfma_f32_32x32x16_bf16 v[98:113], v[216:219], v[224:227], v[98:113]
	s_waitcnt lgkmcnt(3)
	v_mfma_f32_32x32x16_bf16 v[114:129], v[238:241], v[228:231], v[114:129]
	s_waitcnt lgkmcnt(2)
	v_mfma_f32_32x32x16_bf16 v[98:113], v[242:245], v[228:231], v[98:113]
	s_waitcnt lgkmcnt(1)
	v_mfma_f32_32x32x16_bf16 v[114:129], v[246:249], v[232:235], v[114:129]
	s_waitcnt lgkmcnt(0)
	v_mfma_f32_32x32x16_bf16 v[98:113], v[250:253], v[232:235], v[98:113]
	s_cmp_ge_u32 s11, s10
	s_cbranch_scc1 .Lspr_k2
	s_add_i32 s13, s75, 0xe000
	s_mov_b32 s14, m0
	s_mov_b32 m0, s13
	s_nop 0
	global_load_lds_dwordx4 v[170:171], off
	s_mov_b32 m0, s14
.Lspr_k2:
	s_cmp_le_i32 s12, s96
	s_cbranch_scc1 .LBB0_1436
	v_add_u32_e32 v165, 27, v212
	v_cmp_lt_i32_e32 vcc, -1, v165
	s_nop 5
	v_cndmask_b32_e32 v114, v185, v114, vcc
	v_cmp_lt_i32_e32 vcc, 31, v165
	v_add_u32_e32 v165, 26, v212
	s_nop 0
	v_cndmask_b32_e32 v98, v185, v98, vcc
	v_cmp_lt_i32_e32 vcc, -1, v165
	s_nop 1
	v_cndmask_b32_e32 v115, v185, v115, vcc
	v_cmp_lt_i32_e32 vcc, 31, v165
	v_add_u32_e32 v165, 25, v212
	s_nop 0
	v_cndmask_b32_e32 v99, v185, v99, vcc
	v_cmp_lt_i32_e32 vcc, -1, v165
	s_nop 1
	v_cndmask_b32_e32 v116, v185, v116, vcc
	v_cmp_lt_i32_e32 vcc, 31, v165
	v_add_u32_e32 v165, 24, v212
	s_nop 0
	v_cndmask_b32_e32 v100, v185, v100, vcc
	v_cmp_lt_i32_e32 vcc, -1, v165
	s_nop 1
	v_cndmask_b32_e32 v117, v185, v117, vcc
	v_cmp_lt_i32_e32 vcc, 31, v165
	v_add_u32_e32 v165, 19, v212
	s_nop 0
	v_cndmask_b32_e32 v101, v185, v101, vcc
	v_cmp_lt_i32_e32 vcc, -1, v165
	s_nop 1
	v_cndmask_b32_e32 v118, v185, v118, vcc
	v_cmp_lt_i32_e32 vcc, 31, v165
	v_add_u32_e32 v165, 18, v212
	s_nop 0
	v_cndmask_b32_e32 v102, v185, v102, vcc
	v_cmp_lt_i32_e32 vcc, -1, v165
	s_nop 1
	v_cndmask_b32_e32 v119, v185, v119, vcc
	v_cmp_lt_i32_e32 vcc, 31, v165
	v_add_u32_e32 v165, 17, v212
	s_nop 0
	v_cndmask_b32_e32 v103, v185, v103, vcc
	v_cmp_lt_i32_e32 vcc, -1, v165
	s_nop 1
	v_cndmask_b32_e32 v120, v185, v120, vcc
	v_cmp_lt_i32_e32 vcc, 31, v165
	v_add_u32_e32 v165, 16, v212
	s_nop 0
	v_cndmask_b32_e32 v104, v185, v104, vcc
	v_cmp_lt_i32_e32 vcc, -1, v165
	s_nop 1
	v_cndmask_b32_e32 v121, v185, v121, vcc
	v_cmp_lt_i32_e32 vcc, 31, v165
	v_add_u32_e32 v165, 11, v212
	s_nop 0
	v_cndmask_b32_e32 v105, v185, v105, vcc
	v_cmp_lt_i32_e32 vcc, -1, v165
	s_nop 1
	v_cndmask_b32_e32 v122, v185, v122, vcc
	v_cmp_lt_i32_e32 vcc, 31, v165
	v_add_u32_e32 v165, 10, v212
	s_nop 0
	v_cndmask_b32_e32 v106, v185, v106, vcc
	v_cmp_lt_i32_e32 vcc, -1, v165
	s_nop 1
	v_cndmask_b32_e32 v123, v185, v123, vcc
	v_cmp_lt_i32_e32 vcc, 31, v165
	v_add_u32_e32 v165, 9, v212
	s_nop 0
	v_cndmask_b32_e32 v107, v185, v107, vcc
	v_cmp_lt_i32_e32 vcc, -1, v165
	s_nop 1
	v_cndmask_b32_e32 v124, v185, v124, vcc
	v_cmp_lt_i32_e32 vcc, 31, v165
	v_add_u32_e32 v165, 8, v212
	s_nop 0
	v_cndmask_b32_e32 v108, v185, v108, vcc
	v_cmp_lt_i32_e32 vcc, -1, v165
	s_nop 1
	v_cndmask_b32_e32 v125, v185, v125, vcc
	v_cmp_lt_i32_e32 vcc, 31, v165
	v_add_u32_e32 v165, 3, v212
	s_nop 0
	v_cndmask_b32_e32 v109, v185, v109, vcc
	v_cmp_lt_i32_e32 vcc, -1, v165
	s_nop 1
	v_cndmask_b32_e32 v126, v185, v126, vcc
	v_cmp_lt_i32_e32 vcc, 31, v165
	v_add_u32_e32 v165, 2, v212
	s_nop 0
	v_cndmask_b32_e32 v110, v185, v110, vcc
	v_cmp_lt_i32_e32 vcc, -1, v165
	s_nop 1
	v_cndmask_b32_e32 v127, v185, v127, vcc
	v_cmp_lt_i32_e32 vcc, 31, v165
	v_add_u32_e32 v165, 1, v212
	s_nop 0
	v_cndmask_b32_e32 v111, v185, v111, vcc
	v_cmp_lt_i32_e32 vcc, -1, v165
	s_nop 1
	v_cndmask_b32_e32 v128, v185, v128, vcc
	v_cmp_lt_i32_e32 vcc, 31, v165
	s_nop 1
	v_cndmask_b32_e32 v112, v185, v112, vcc
	v_cmp_lt_i32_e32 vcc, -1, v212
	s_nop 1
	v_cndmask_b32_e32 v129, v185, v129, vcc
	v_cmp_lt_i32_e32 vcc, 31, v212
	s_nop 1
	v_cndmask_b32_e32 v113, v185, v113, vcc

.LBB0_1440:
	v_exp_f32_e32 v114, v114
	v_exp_f32_e32 v167, v98
	v_exp_f32_e32 v98, v115
	v_exp_f32_e32 v115, v99
	v_exp_f32_e32 v99, v116
	v_exp_f32_e32 v116, v100
	v_exp_f32_e32 v100, v117
	v_exp_f32_e32 v117, v101
	v_exp_f32_e32 v101, v118
	v_exp_f32_e32 v118, v102
	v_exp_f32_e32 v102, v119
	v_exp_f32_e32 v119, v103
	v_exp_f32_e32 v103, v120
	v_exp_f32_e32 v120, v104
	v_exp_f32_e32 v104, v121
	v_exp_f32_e32 v121, v105
	v_exp_f32_e32 v105, v122
	v_exp_f32_e32 v122, v106
	v_exp_f32_e32 v106, v123
	v_exp_f32_e32 v123, v107
	v_exp_f32_e32 v107, v124
	v_exp_f32_e32 v124, v108
	v_exp_f32_e32 v108, v125
	v_exp_f32_e32 v125, v109
	v_exp_f32_e32 v109, v126
	v_exp_f32_e32 v126, v110
	v_exp_f32_e32 v110, v127
	v_exp_f32_e32 v127, v111
	v_exp_f32_e32 v111, v128
	v_exp_f32_e32 v128, v112
	v_exp_f32_e32 v112, v129
	v_add_f32_e32 v129, v114, v167
	v_add_f32_e32 v178, v98, v115
	v_add_f32_e32 v179, v99, v116
	v_add_f32_e32 v180, v100, v117
	v_exp_f32_e32 v113, v113
	v_add_f32_e32 v129, v129, v101
	v_add_f32_e32 v178, v178, v102
	v_add_f32_e32 v179, v179, v103
	v_add_f32_e32 v180, v180, v104
	v_cvt_pk_bf16_f32 v98, v114, v98
	v_cvt_pk_bf16_f32 v99, v99, v100
	s_nop 0
	v_add_f32_e32 v129, v129, v118
	v_add_f32_e32 v178, v178, v119
	v_add_f32_e32 v179, v179, v120
	v_add_f32_e32 v180, v180, v121
	v_cvt_pk_bf16_f32 v100, v101, v102
	v_cvt_pk_bf16_f32 v101, v103, v104
	s_nop 0
	v_add_f32_e32 v129, v129, v105
	v_add_f32_e32 v178, v178, v106
	v_add_f32_e32 v179, v179, v107
	v_add_f32_e32 v180, v180, v108
	v_cvt_pk_bf16_f32 v102, v105, v106
	v_cvt_pk_bf16_f32 v103, v107, v108
	s_nop 0
	v_add_f32_e32 v129, v129, v122
	v_add_f32_e32 v178, v178, v123
	v_add_f32_e32 v179, v179, v124
	v_add_f32_e32 v180, v180, v125
	v_cvt_pk_bf16_f32 v104, v109, v110
	v_cvt_pk_bf16_f32 v105, v111, v112
	s_nop 0
	v_add_f32_e32 v129, v129, v109
	v_add_f32_e32 v178, v178, v110
	v_add_f32_e32 v179, v179, v111
	v_add_f32_e32 v180, v180, v112
	v_cvt_pk_bf16_f32 v106, v167, v115
	v_cvt_pk_bf16_f32 v107, v116, v117
	s_nop 0
	v_add_f32_e32 v129, v129, v126
	v_add_f32_e32 v178, v178, v127
	v_add_f32_e32 v179, v179, v128
	v_add_f32_e32 v180, v180, v113
	v_cvt_pk_bf16_f32 v108, v118, v119
	v_cvt_pk_bf16_f32 v109, v120, v121
	v_cvt_pk_bf16_f32 v110, v122, v123
	s_nop 0
	v_add_f32_e32 v129, v129, v178
	v_cvt_pk_bf16_f32 v111, v124, v125
	v_add_f32_e32 v178, v179, v180
	v_cvt_pk_bf16_f32 v112, v126, v127
	v_cvt_pk_bf16_f32 v113, v128, v113
	v_permlane32_swap_b32_e32 v98, v100
	v_add_f32_e32 v129, v129, v178
	v_permlane32_swap_b32_e32 v99, v101
	v_mov_b32_e32 v178, v129
	s_nop 1
	v_permlane32_swap_b32_e32 v129, v178
	v_add_f32_e32 v129, v129, v178
	v_add_f32_e32 v199, v165, v129
	v_permlane32_swap_b32_e32 v102, v104
	v_permlane32_swap_b32_e32 v103, v105
	v_permlane32_swap_b32_e32 v106, v108
	v_permlane32_swap_b32_e32 v107, v109
	v_permlane32_swap_b32_e32 v110, v112
	v_permlane32_swap_b32_e32 v111, v113
	s_cmp_ge_u32 s11, s10
	s_cbranch_scc1 .Lspr_k3
	s_add_i32 s13, s5, 0xe000
	s_mov_b32 s14, m0
	s_mov_b32 m0, s13
	s_nop 0
	global_load_lds_dwordx4 v[172:173], off
	s_mov_b32 m0, s14
	v_mov_b32_e32 v165, v163
	v_mov_b32_e32 v167, v163
	v_lshl_add_u64 v[168:169], v[168:169], 0, v[162:163]
	v_lshl_add_u64 v[170:171], v[170:171], 0, v[164:165]
	v_lshl_add_u64 v[172:173], v[172:173], 0, v[166:167]
.Lspr_k3:
	ds_read_b64_tr_b16 v[114:115], v190 offset:0
	ds_read_b64_tr_b16 v[116:117], v190 offset:0x800
	ds_read_b64_tr_b16 v[118:119], v190 offset:0x1000
	ds_read_b64_tr_b16 v[120:121], v190 offset:0x1800
	ds_read_b64_tr_b16 v[122:123], v190 offset:0x2000
	ds_read_b64_tr_b16 v[124:125], v190 offset:0x2800
	ds_read_b64_tr_b16 v[126:127], v190 offset:0x3000
	ds_read_b64_tr_b16 v[128:129], v190 offset:0x3800
	ds_read_b64_tr_b16 v[178:179], v190 offset:0x200
	ds_read_b64_tr_b16 v[180:181], v190 offset:0xa00
	ds_read_b64_tr_b16 v[214:215], v190 offset:0x1200
	ds_read_b64_tr_b16 v[216:217], v190 offset:0x1a00
	ds_read_b64_tr_b16 v[218:219], v190 offset:0x2200
	ds_read_b64_tr_b16 v[220:221], v190 offset:0x2a00
	ds_read_b64_tr_b16 v[222:223], v190 offset:0x3200
	ds_read_b64_tr_b16 v[224:225], v190 offset:0x3a00
	s_waitcnt lgkmcnt(8)
	s_nop 0
	v_mfma_f32_32x32x16_bf16 v[18:33], v[98:101], v[114:117], v[18:33]
	v_mfma_f32_32x32x16_bf16 v[18:33], v[102:105], v[118:121], v[18:33]
	v_mfma_f32_32x32x16_bf16 v[18:33], v[106:109], v[122:125], v[18:33]
	v_mfma_f32_32x32x16_bf16 v[18:33], v[110:113], v[126:129], v[18:33]
	ds_read_b64_tr_b16 v[114:115], v190 offset:0x400
	ds_read_b64_tr_b16 v[116:117], v190 offset:0xc00
	ds_read_b64_tr_b16 v[118:119], v190 offset:0x1400
	ds_read_b64_tr_b16 v[120:121], v190 offset:0x1c00
	ds_read_b64_tr_b16 v[122:123], v190 offset:0x2400
	ds_read_b64_tr_b16 v[124:125], v190 offset:0x2c00
	ds_read_b64_tr_b16 v[126:127], v190 offset:0x3400
	ds_read_b64_tr_b16 v[128:129], v190 offset:0x3c00
	s_waitcnt lgkmcnt(8)
	v_mfma_f32_32x32x16_bf16 v[34:49], v[98:101], v[178:181], v[34:49]
	v_mfma_f32_32x32x16_bf16 v[34:49], v[102:105], v[214:217], v[34:49]
	v_mfma_f32_32x32x16_bf16 v[34:49], v[106:109], v[218:221], v[34:49]
	v_mfma_f32_32x32x16_bf16 v[34:49], v[110:113], v[222:225], v[34:49]
	ds_read_b64_tr_b16 v[178:179], v190 offset:0x600
	ds_read_b64_tr_b16 v[180:181], v190 offset:0xe00
	ds_read_b64_tr_b16 v[214:215], v190 offset:0x1600
	ds_read_b64_tr_b16 v[216:217], v190 offset:0x1e00
	ds_read_b64_tr_b16 v[218:219], v190 offset:0x2600
	ds_read_b64_tr_b16 v[220:221], v190 offset:0x2e00
	ds_read_b64_tr_b16 v[222:223], v190 offset:0x3600
	ds_read_b64_tr_b16 v[224:225], v190 offset:0x3e00
	s_waitcnt lgkmcnt(8)
	v_mfma_f32_32x32x16_bf16 v[50:65], v[98:101], v[114:117], v[50:65]
	v_mfma_f32_32x32x16_bf16 v[50:65], v[102:105], v[118:121], v[50:65]
	v_mfma_f32_32x32x16_bf16 v[50:65], v[106:109], v[122:125], v[50:65]
	v_mfma_f32_32x32x16_bf16 v[50:65], v[110:113], v[126:129], v[50:65]
	s_waitcnt lgkmcnt(0)
	v_mfma_f32_32x32x16_bf16 v[66:81], v[98:101], v[178:181], v[66:81]
	s_waitcnt vmcnt(0)
	s_addk_i32 s12, 0x80
	s_add_i32 s8, s11, 2
	s_add_i32 s9, s11, 1
	v_add_u32_e32 v212, 0xffffff80, v212
	s_cmp_lt_u32 s9, s10
	v_mfma_f32_32x32x16_bf16 v[66:81], v[102:105], v[214:217], v[66:81]
	s_barrier
	v_mfma_f32_32x32x16_bf16 v[66:81], v[106:109], v[218:221], v[66:81]
	v_mfma_f32_32x32x16_bf16 v[66:81], v[110:113], v[222:225], v[66:81]
	s_cbranch_scc0 .LBB0_1442
	s_mov_b32 s11, s8
	s_branch .LBB0_1425
